# attention KV loop: QK^T K-fragment reads via 5-quad ring, PV V^T reads via 3-quad ring (LDS latency hidden); plus RWKV chain/forward-substitution prefetch
# baseline (speedup 1.0000x reference)
; template <bool NOSTORE> __device__ __forceinline__ void attn_mfma_item(const Frame& F, ArgsRef A, int l, int item) {
;     ...
; #pragma unroll
;         for (int s = 0; s < 8; ++s) {
;             const bf16x8 k0 = LD_(bf16x8, a_kf + 32 * s), k1 = LD_(bf16x8, a_kf + 32 * AK_LD * 2 + 32 * s);
;             sc0 = __builtin_amdgcn_mfma_f32_32x32x16_bf16(k0, qf[s], sc0, 0, 0, 0);
;             sc1 = __builtin_amdgcn_mfma_f32_32x32x16_bf16(k1, qf[s], sc1, 0, 0, 0);
;         }
;         float tmax = -3.0e38f;
;         if (cur < 5) {
;             const int kbase = t0 - 128 + 64 * cur - tq + 4 * g;
; #pragma unroll
;             for (int r = 0; r < 16; ++r) { const int d0 = kbase + 8 * (r >> 2) + (r & 3), d1 = d0 + 32;
;                 sc0[r] = (d0 >= -128 && d0 <= 128) ? sc0[r] * C2 : -1.0e30f; sc1[r] = (d1 >= -128 && d1 <= 128) ? sc1[r] * C2 : -1.0e30f; }
;         } else {
; #pragma unroll
;             for (int r = 0; r < 16; ++r) { sc0[r] *= C2; sc1[r] *= C2; }
;         }
.LBB0_852:
	ds_read_b128 v[4:7], v250 offset:8704
	ds_read_b128 v[8:11], v250
	ds_read_b128 v[12:15], v250 offset:32
	ds_read_b128 v[196:199], v250 offset:8736
	ds_read_b128 v[228:231], v250 offset:64
	s_mov_b64 s[20:21], -1
	s_andn2_b64 vcc, exec, s[18:19]
	s_waitcnt lgkmcnt(4)
	v_mfma_f32_32x32x16_bf16 v[112:127], v[4:7], v[144:147], 0
	ds_read_b128 v[4:7], v250 offset:8768
	s_waitcnt lgkmcnt(4)
	v_mfma_f32_32x32x16_bf16 v[128:143], v[8:11], v[144:147], 0
	ds_read_b128 v[8:11], v250 offset:96
	s_waitcnt lgkmcnt(4)
	v_mfma_f32_32x32x16_bf16 v[128:143], v[12:15], v[148:151], v[128:143]
	ds_read_b128 v[12:15], v250 offset:8800
	s_waitcnt lgkmcnt(4)
	v_mfma_f32_32x32x16_bf16 v[112:127], v[196:199], v[148:151], v[112:127]
	ds_read_b128 v[196:199], v250 offset:128
	s_waitcnt lgkmcnt(4)
	v_mfma_f32_32x32x16_bf16 v[128:143], v[228:231], v[152:155], v[128:143]
	ds_read_b128 v[228:231], v250 offset:8832
	s_waitcnt lgkmcnt(4)
	v_mfma_f32_32x32x16_bf16 v[112:127], v[4:7], v[152:155], v[112:127]
	ds_read_b128 v[4:7], v250 offset:160
	s_waitcnt lgkmcnt(4)
	v_mfma_f32_32x32x16_bf16 v[128:143], v[8:11], v[156:159], v[128:143]
	ds_read_b128 v[8:11], v250 offset:8864
	s_waitcnt lgkmcnt(4)
	v_mfma_f32_32x32x16_bf16 v[112:127], v[12:15], v[156:159], v[112:127]
	ds_read_b128 v[12:15], v250 offset:192
	s_waitcnt lgkmcnt(4)
	v_mfma_f32_32x32x16_bf16 v[128:143], v[196:199], v[160:163], v[128:143]
	ds_read_b128 v[196:199], v250 offset:8896
	s_waitcnt lgkmcnt(4)
	v_mfma_f32_32x32x16_bf16 v[112:127], v[228:231], v[160:163], v[112:127]
	ds_read_b128 v[228:231], v250 offset:224
	s_waitcnt lgkmcnt(4)
	v_mfma_f32_32x32x16_bf16 v[128:143], v[4:7], v[164:167], v[128:143]
	ds_read_b128 v[4:7], v250 offset:8928
	s_waitcnt lgkmcnt(4)
	v_mfma_f32_32x32x16_bf16 v[112:127], v[8:11], v[164:167], v[112:127]
	s_waitcnt lgkmcnt(3)
	v_mfma_f32_32x32x16_bf16 v[128:143], v[12:15], v[168:171], v[128:143]
	s_waitcnt lgkmcnt(2)
	v_mfma_f32_32x32x16_bf16 v[112:127], v[196:199], v[168:171], v[112:127]
	s_waitcnt lgkmcnt(1)
	v_mfma_f32_32x32x16_bf16 v[128:143], v[228:231], v[172:175], v[128:143]
	s_waitcnt lgkmcnt(0)
	v_mfma_f32_32x32x16_bf16 v[112:127], v[4:7], v[172:175], v[112:127]
	s_cbranch_vccnz .LBB0_854
	s_nop 8
	v_pk_mul_f32 v[94:95], v[142:143], s[56:57] op_sel_hi:[1,0]
	v_pk_mul_f32 v[92:93], v[140:141], s[56:57] op_sel_hi:[1,0]
	v_pk_mul_f32 v[90:91], v[138:139], s[56:57] op_sel_hi:[1,0]
	v_pk_mul_f32 v[88:89], v[136:137], s[56:57] op_sel_hi:[1,0]
	v_pk_mul_f32 v[86:87], v[134:135], s[56:57] op_sel_hi:[1,0]
	v_pk_mul_f32 v[84:85], v[132:133], s[56:57] op_sel_hi:[1,0]
	v_pk_mul_f32 v[82:83], v[130:131], s[56:57] op_sel_hi:[1,0]
	v_pk_mul_f32 v[80:81], v[128:129], s[56:57] op_sel_hi:[1,0]
	v_pk_mul_f32 v[110:111], v[126:127], s[56:57] op_sel_hi:[1,0]
	v_pk_mul_f32 v[108:109], v[124:125], s[56:57] op_sel_hi:[1,0]
	v_pk_mul_f32 v[106:107], v[122:123], s[56:57] op_sel_hi:[1,0]
	v_pk_mul_f32 v[104:105], v[120:121], s[56:57] op_sel_hi:[1,0]
	v_pk_mul_f32 v[102:103], v[118:119], s[56:57] op_sel_hi:[1,0]
	v_pk_mul_f32 v[100:101], v[116:117], s[56:57] op_sel_hi:[1,0]
	v_pk_mul_f32 v[98:99], v[114:115], s[56:57] op_sel_hi:[1,0]
	v_pk_mul_f32 v[96:97], v[112:113], s[56:57] op_sel_hi:[1,0]
	s_mov_b64 s[20:21], 0

; __device__ __forceinline__ float xhalf_max(float v) { float a = v, b = v; half_swap(a, b); return fmaxf(a, b); }
; __device__ __forceinline__ unsigned cvt_pk_bf16(float lo, float hi) { const f2_t_ v = {lo, hi}; return __builtin_bit_cast(unsigned, __builtin_convertvector(v, bf2_t_)); }
; template <bool NOSTORE> __device__ __forceinline__ void attn_mfma_item(const Frame& F, ArgsRef A, int l, int item) {
;     ...
; #pragma unroll
;         for (int r = 0; r < 16; ++r) tmax = fmaxf(tmax, fmaxf(sc0[r], sc1[r]));
;         tmax = xhalf_max(tmax);
;         const float mnew = fmaxf(mrun, tmax);
;         const float corr = __builtin_amdgcn_exp2f(mrun - mnew);
;         mrun = mnew;
;         float ps = 0.f;
; #pragma unroll
;         for (int r = 0; r < 16; ++r) { sc0[r] = __builtin_amdgcn_exp2f(sc0[r] - mnew); sc1[r] = __builtin_amdgcn_exp2f(sc1[r] - mnew); ps += sc0[r] + sc1[r]; }
;         lsum = lsum * corr + ps;
;         if (__builtin_amdgcn_ballot_w64(corr != 1.0f) != 0ull) {
; #pragma unroll
;             for (int mt = 0; mt < 4; ++mt)
; #pragma unroll
;                 for (int r = 0; r < 16; ++r) O[mt][r] *= corr;
;         }
; #pragma unroll
;         for (int u = 0; u < 2; ++u)
; #pragma unroll
;             for (int s = 0; s < 2; ++s) {
;                 v4u pw;
;                 if (u == 0) { pw.x = pg8::cvt_pk_bf16(sc0[8 * s + 0], sc0[8 * s + 1]); pw.y = pg8::cvt_pk_bf16(sc0[8 * s + 2], sc0[8 * s + 3]); pw.z = pg8::cvt_pk_bf16(sc0[8 * s + 4], sc0[8 * s + 5]); pw.w = pg8::cvt_pk_bf16(sc0[8 * s + 6], sc0[8 * s + 7]); }
;                 else { pw.x = pg8::cvt_pk_bf16(sc1[8 * s + 0], sc1[8 * s + 1]); pw.y = pg8::cvt_pk_bf16(sc1[8 * s + 2], sc1[8 * s + 3]); pw.z = pg8::cvt_pk_bf16(sc1[8 * s + 4], sc1[8 * s + 5]); pw.w = pg8::cvt_pk_bf16(sc1[8 * s + 6], sc1[8 * s + 7]); }
;                 const bf16x8 pb = __builtin_bit_cast(bf16x8, pw);
; #pragma unroll
;                 for (int mt = 0; mt < 4; ++mt) {
;                     const bf16x8 av = tr8(L, a_vf + ((32 * u + 16 * s) * AV_LD + 32 * mt) * 2, a_vf + ((32 * u + 16 * s + 8) * AV_LD + 32 * mt) * 2);
;                     O[mt] = __builtin_amdgcn_mfma_f32_32x32x16_bf16(av, pb, O[mt], 0, 0, 0);
;                 }
;             }
;         tile = nxt;
.LBB0_858:
	v_sub_f32_e32 v4, v80, v1
	v_sub_f32_e32 v5, v96, v1
	v_exp_f32_e32 v4, v4
	v_exp_f32_e32 v15, v5
	v_sub_f32_e32 v6, v81, v1
	v_sub_f32_e32 v7, v97, v1
	v_exp_f32_e32 v6, v6
	v_exp_f32_e32 v96, v7
	v_add_f32_e32 v5, v4, v15
	v_add_f32_e32 v5, 0, v5
	v_sub_f32_e32 v8, v98, v1
	v_add_f32_e32 v7, v6, v96
	v_add_f32_e32 v5, v7, v5
	v_sub_f32_e32 v7, v82, v1
	v_exp_f32_e32 v7, v7
	v_exp_f32_e32 v82, v8
	v_cvt_pk_bf16_f32 v4, v4, v6
	s_andn2_b64 vcc, exec, s[16:17]
	v_add_f32_e32 v8, v7, v82
	v_add_f32_e32 v5, v8, v5
	v_sub_f32_e32 v8, v83, v1
	v_exp_f32_e32 v97, v8
	v_sub_f32_e32 v8, v99, v1
	v_exp_f32_e32 v83, v8
	s_nop 0
	v_add_f32_e32 v8, v97, v83
	v_add_f32_e32 v5, v8, v5
	v_sub_f32_e32 v8, v84, v1
	v_exp_f32_e32 v98, v8
	v_sub_f32_e32 v8, v100, v1
	v_exp_f32_e32 v84, v8
	s_nop 0
	v_add_f32_e32 v8, v98, v84
	v_add_f32_e32 v5, v8, v5
	v_sub_f32_e32 v8, v85, v1
	v_exp_f32_e32 v99, v8
	v_sub_f32_e32 v8, v101, v1
	v_exp_f32_e32 v85, v8
	v_cvt_pk_bf16_f32 v6, v98, v99
	v_add_f32_e32 v8, v99, v85
	v_add_f32_e32 v5, v8, v5
	v_sub_f32_e32 v8, v86, v1
	v_exp_f32_e32 v100, v8
	v_sub_f32_e32 v8, v102, v1
	v_exp_f32_e32 v86, v8
	s_nop 0
	v_add_f32_e32 v8, v100, v86
	v_add_f32_e32 v5, v8, v5
	v_sub_f32_e32 v8, v87, v1
	v_exp_f32_e32 v101, v8
	v_sub_f32_e32 v8, v103, v1
	v_exp_f32_e32 v87, v8
	s_nop 0
	v_add_f32_e32 v8, v101, v87
	v_add_f32_e32 v5, v8, v5
	v_sub_f32_e32 v8, v88, v1
	v_exp_f32_e32 v102, v8
	v_sub_f32_e32 v8, v104, v1
	v_exp_f32_e32 v9, v8
	s_nop 0
	v_add_f32_e32 v8, v102, v9
	v_add_f32_e32 v5, v8, v5
	v_sub_f32_e32 v8, v89, v1
	v_exp_f32_e32 v103, v8
	v_sub_f32_e32 v8, v105, v1
	v_exp_f32_e32 v10, v8
	s_nop 0
	v_add_f32_e32 v8, v103, v10
	v_add_f32_e32 v5, v8, v5
	v_sub_f32_e32 v8, v90, v1
	v_exp_f32_e32 v104, v8
	v_sub_f32_e32 v8, v106, v1
	v_exp_f32_e32 v11, v8
	s_nop 0
	v_add_f32_e32 v8, v104, v11
	v_add_f32_e32 v5, v8, v5
	v_sub_f32_e32 v8, v91, v1
	v_exp_f32_e32 v105, v8
	v_sub_f32_e32 v8, v107, v1
	v_exp_f32_e32 v12, v8
	ds_read_b64_tr_b16 v[88:89], v251
	ds_read_b64_tr_b16 v[90:91], v251 offset:2176
	ds_read_b64_tr_b16 v[196:197], v251 offset:64
	ds_read_b64_tr_b16 v[198:199], v251 offset:2240
	ds_read_b64_tr_b16 v[228:229], v251 offset:128
	ds_read_b64_tr_b16 v[230:231], v251 offset:2304
	v_add_f32_e32 v8, v105, v12
	v_add_f32_e32 v5, v8, v5
	v_sub_f32_e32 v8, v92, v1
	v_exp_f32_e32 v92, v8
	v_sub_f32_e32 v8, v108, v1
	v_exp_f32_e32 v13, v8
	s_nop 0
	v_add_f32_e32 v8, v92, v13
	v_add_f32_e32 v5, v8, v5
	v_sub_f32_e32 v8, v93, v1
	v_exp_f32_e32 v93, v8
	v_sub_f32_e32 v8, v109, v1
	v_exp_f32_e32 v14, v8
	s_nop 0
	v_add_f32_e32 v8, v93, v14
	v_add_f32_e32 v5, v8, v5
	v_sub_f32_e32 v8, v94, v1
	v_exp_f32_e32 v94, v8
	v_sub_f32_e32 v8, v110, v1
	v_exp_f32_e32 v80, v8
	s_nop 0
	v_add_f32_e32 v8, v94, v80
	v_add_f32_e32 v5, v8, v5
	v_sub_f32_e32 v8, v95, v1
	v_exp_f32_e32 v95, v8
	v_sub_f32_e32 v8, v111, v1
	v_exp_f32_e32 v81, v8
	s_nop 0
	v_add_f32_e32 v8, v95, v81
	v_add_f32_e32 v8, v8, v5
	v_cvt_pk_bf16_f32 v5, v7, v97
	v_cvt_pk_bf16_f32 v7, v100, v101
	v_fmac_f32_e32 v8, v3, v0
	s_waitcnt lgkmcnt(4)
	v_mfma_f32_32x32x16_bf16 v[64:79], v[88:91], v[4:7], v[64:79]
	ds_read_b64_tr_b16 v[88:89], v251 offset:192
	ds_read_b64_tr_b16 v[90:91], v251 offset:2368
	s_waitcnt lgkmcnt(4)
	v_mfma_f32_32x32x16_bf16 v[48:63], v[196:199], v[4:7], v[48:63]
	ds_read_b64_tr_b16 v[196:197], v251 offset:4352
	ds_read_b64_tr_b16 v[198:199], v251 offset:6528
	s_waitcnt lgkmcnt(4)
	v_mfma_f32_32x32x16_bf16 v[32:47], v[228:231], v[4:7], v[32:47]
	ds_read_b64_tr_b16 v[228:229], v251 offset:4416
	ds_read_b64_tr_b16 v[230:231], v251 offset:6592
	s_waitcnt lgkmcnt(4)
	v_mfma_f32_32x32x16_bf16 v[16:31], v[88:91], v[4:7], v[16:31]
	ds_read_b64_tr_b16 v[88:89], v251 offset:4480
	ds_read_b64_tr_b16 v[90:91], v251 offset:6656
	v_cvt_pk_bf16_f32 v4, v102, v103
	v_cvt_pk_bf16_f32 v5, v104, v105
	v_cvt_pk_bf16_f32 v6, v92, v93
	v_cvt_pk_bf16_f32 v7, v94, v95
	s_waitcnt lgkmcnt(4)
	s_nop 0
	v_mfma_f32_32x32x16_bf16 v[64:79], v[196:199], v[4:7], v[64:79]
	ds_read_b64_tr_b16 v[196:197], v251 offset:4544
	ds_read_b64_tr_b16 v[198:199], v251 offset:6720
	s_waitcnt lgkmcnt(4)
	v_mfma_f32_32x32x16_bf16 v[48:63], v[228:231], v[4:7], v[48:63]
	ds_read_b64_tr_b16 v[228:229], v251 offset:8704
	ds_read_b64_tr_b16 v[230:231], v251 offset:10880
	s_waitcnt lgkmcnt(4)
	v_mfma_f32_32x32x16_bf16 v[32:47], v[88:91], v[4:7], v[32:47]
	ds_read_b64_tr_b16 v[88:89], v251 offset:8768
	ds_read_b64_tr_b16 v[90:91], v251 offset:10944
	s_waitcnt lgkmcnt(4)
	v_mfma_f32_32x32x16_bf16 v[16:31], v[196:199], v[4:7], v[16:31]
	ds_read_b64_tr_b16 v[196:197], v251 offset:8832
	ds_read_b64_tr_b16 v[198:199], v251 offset:11008
	v_cvt_pk_bf16_f32 v5, v82, v83
	v_cvt_pk_bf16_f32 v6, v84, v85
	v_cvt_pk_bf16_f32 v4, v15, v96
	v_cvt_pk_bf16_f32 v7, v86, v87
	s_waitcnt lgkmcnt(4)
	s_nop 0
	v_mfma_f32_32x32x16_bf16 v[64:79], v[228:231], v[4:7], v[64:79]
	ds_read_b64_tr_b16 v[228:229], v251 offset:8896
	ds_read_b64_tr_b16 v[230:231], v251 offset:11072
	s_waitcnt lgkmcnt(4)
	v_mfma_f32_32x32x16_bf16 v[48:63], v[88:91], v[4:7], v[48:63]
	ds_read_b64_tr_b16 v[88:89], v251 offset:13056
	ds_read_b64_tr_b16 v[90:91], v251 offset:15232
	s_waitcnt lgkmcnt(4)
	v_mfma_f32_32x32x16_bf16 v[32:47], v[196:199], v[4:7], v[32:47]
	ds_read_b64_tr_b16 v[196:197], v251 offset:13120
	ds_read_b64_tr_b16 v[198:199], v251 offset:15296
	s_waitcnt lgkmcnt(4)
	v_mfma_f32_32x32x16_bf16 v[16:31], v[228:231], v[4:7], v[16:31]
	ds_read_b64_tr_b16 v[228:229], v251 offset:13184
	ds_read_b64_tr_b16 v[230:231], v251 offset:15360
	v_cvt_pk_bf16_f32 v4, v9, v10
	v_cvt_pk_bf16_f32 v5, v11, v12
	v_cvt_pk_bf16_f32 v6, v13, v14
	v_cvt_pk_bf16_f32 v7, v80, v81
	s_waitcnt lgkmcnt(4)
	s_nop 0
	v_mfma_f32_32x32x16_bf16 v[64:79], v[88:91], v[4:7], v[64:79]
	ds_read_b64_tr_b16 v[88:89], v251 offset:13248
	ds_read_b64_tr_b16 v[90:91], v251 offset:15424
	s_waitcnt lgkmcnt(4)
	v_mfma_f32_32x32x16_bf16 v[48:63], v[196:199], v[4:7], v[48:63]
	s_waitcnt lgkmcnt(2)
	v_mfma_f32_32x32x16_bf16 v[32:47], v[228:231], v[4:7], v[32:47]
	s_waitcnt lgkmcnt(0)
	v_mfma_f32_32x32x16_bf16 v[16:31], v[88:91], v[4:7], v[16:31]
	s_cbranch_vccz .LBB0_824
	v_mov_b32_e32 v252, v1
	v_mov_b32_e32 v3, v8
	s_mov_b32 s28, s27
	s_branch .LBB0_844
